# P2 K-loop: waves 4-7 staggered half a K-step behind waves 0-3 (barrier between their ks0 and ks1 blocks)
# baseline (speedup 1.0000x reference)
.LBB0_465:
	s_mul_hi_i32 s4, s20, 0x38e38e39
	s_lshr_b32 s6, s4, 31
	s_ashr_i32 s4, s4, 4
	s_add_i32 s4, s4, s6
	s_mul_i32 s6, s4, 0x48
	s_sub_i32 s6, s20, s6
	s_lshl_b32 s6, s6, 8
	v_add_u32_e32 v2, s6, v204
	v_ashrrev_i32_e32 v3, 31, v2
	v_lshlrev_b64 v[2:3], 11, v[2:3]
	v_lshl_add_u64 v[168:169], v[162:163], 0, v[2:3]
	v_add_co_u32_e32 v56, vcc, s34, v168
	s_lshl_b32 s7, s4, 8
	s_nop 0
	v_addc_co_u32_e32 v57, vcc, 0, v169, vcc
	v_add_u32_e32 v2, s7, v204
	s_waitcnt vmcnt(9)
	v_add_co_u32_e32 v58, vcc, s35, v168
	v_ashrrev_i32_e32 v3, 31, v2
	s_nop 0
	v_addc_co_u32_e32 v59, vcc, 0, v169, vcc
	v_lshlrev_b64 v[2:3], 11, v[2:3]
	v_add_co_u32_e32 v60, vcc, s36, v168
	v_lshl_add_u64 v[170:171], v[164:165], 0, v[2:3]
	s_nop 0
	v_addc_co_u32_e32 v61, vcc, 0, v169, vcc
	s_waitcnt vmcnt(8)
	v_add_co_u32_e32 v62, vcc, s35, v170
	global_load_dwordx4 v[24:27], v[56:57], off
	global_load_dwordx4 v[28:31], v[58:59], off
	v_addc_co_u32_e32 v63, vcc, 0, v171, vcc
	v_add_co_u32_e32 v64, vcc, s36, v170
	global_load_dwordx4 v[32:35], v[168:169], off
	global_load_dwordx4 v[36:39], v[170:171], off
	v_addc_co_u32_e32 v65, vcc, 0, v171, vcc
	v_add_co_u32_e32 v66, vcc, s34, v170
	global_load_dwordx4 v[40:43], v[62:63], off
	global_load_dwordx4 v[44:47], v[64:65], off
	v_addc_co_u32_e32 v67, vcc, 0, v171, vcc
	global_load_dwordx4 v[48:51], v[60:61], off
	global_load_dwordx4 v[52:55], v[66:67], off
	s_barrier
	global_load_dwordx4 v[114:117], v[168:169], off offset:128
	global_load_dwordx4 v[106:109], v[56:57], off offset:128
	global_load_dwordx4 v[110:113], v[58:59], off offset:128
	global_load_dwordx4 v[126:129], v[60:61], off offset:128
	global_load_dwordx4 v[122:125], v[170:171], off offset:128
	global_load_dwordx4 v[118:121], v[66:67], off offset:128
	global_load_dwordx4 v[134:137], v[62:63], off offset:128
	global_load_dwordx4 v[130:133], v[64:65], off offset:128
	v_readfirstlane_b32 s100, v172
	s_nop 0
	s_lshr_b32 m0, s100, 8
	v_readfirstlane_b32 vcc_lo, v168
	v_readfirstlane_b32 vcc_hi, v169
	v_readfirstlane_b32 s100, v170
	v_readfirstlane_b32 s101, v171
	s_nop 1
	v_subrev_u32_e32 v168, vcc_lo, v168
	v_subrev_u32_e32 v170, s100, v170
	v_mov_b32_e32 v2, 0
	s_mov_b32 s4, 0
	v_mov_b32_e32 v3, v2
	v_mov_b32_e32 v4, v2
	v_mov_b32_e32 v5, v2
	v_mov_b32_e32 v6, v2
	v_mov_b32_e32 v7, v2
	v_mov_b32_e32 v8, v2
	v_mov_b32_e32 v9, v2
	v_mov_b32_e32 v10, v2
	v_mov_b32_e32 v11, v2
	v_mov_b32_e32 v12, v2
	v_mov_b32_e32 v13, v2
	v_mov_b32_e32 v14, v2
	v_mov_b32_e32 v15, v2
	v_mov_b32_e32 v16, v2
	v_mov_b32_e32 v17, v2
	v_mov_b32_e32 v18, v2
	v_mov_b32_e32 v19, v2
	v_mov_b32_e32 v20, v2
	v_mov_b32_e32 v21, v2
	v_mov_b32_e32 v22, v2
	v_mov_b32_e32 v23, v2
	v_mov_b32_e32 v56, v2
	v_mov_b32_e32 v57, v2
	v_mov_b32_e32 v58, v2
	v_mov_b32_e32 v59, v2
	v_mov_b32_e32 v60, v2
	v_mov_b32_e32 v61, v2
	v_mov_b32_e32 v62, v2
	v_mov_b32_e32 v63, v2
	v_mov_b32_e32 v64, v2
	v_mov_b32_e32 v65, v2
	v_mov_b32_e32 v66, v2
	v_mov_b32_e32 v67, v2
	v_mov_b32_e32 v68, v2
	v_mov_b32_e32 v69, v2
	v_mov_b32_e32 v70, v2
	v_mov_b32_e32 v71, v2
	v_mov_b32_e32 v72, v2
	v_mov_b32_e32 v73, v2
	v_mov_b32_e32 v74, v2
	v_mov_b32_e32 v75, v2
	v_mov_b32_e32 v76, v2
	v_mov_b32_e32 v77, v2
	v_mov_b32_e32 v78, v2
	v_mov_b32_e32 v79, v2
	v_mov_b32_e32 v80, v2
	v_mov_b32_e32 v81, v2
	v_mov_b32_e32 v82, v2
	v_mov_b32_e32 v83, v2
	v_mov_b32_e32 v84, v2
	v_mov_b32_e32 v85, v2
	s_waitcnt vmcnt(11)
	ds_write_b128 v166, v[40:43] offset:49152
	s_waitcnt vmcnt(10)
	ds_write_b128 v166, v[44:47] offset:57344
	ds_write_b128 v166, v[32:35]
	ds_write_b128 v166, v[36:39] offset:32768
	ds_write_b128 v166, v[24:27] offset:8192
	ds_write_b128 v166, v[28:31] offset:16384
	s_waitcnt vmcnt(9)
	ds_write_b128 v166, v[48:51] offset:24576
	s_waitcnt vmcnt(8)
	ds_write_b128 v166, v[52:55] offset:40960
	v_mov_b32_e32 v24, v2
	v_mov_b32_e32 v25, v2
	v_mov_b32_e32 v26, v2
	v_mov_b32_e32 v27, v2
	v_mov_b32_e32 v28, v2
	v_mov_b32_e32 v29, v2
	v_mov_b32_e32 v30, v2
	v_mov_b32_e32 v31, v2
	v_mov_b32_e32 v32, v2
	v_mov_b32_e32 v33, v2
	v_mov_b32_e32 v34, v2
	v_mov_b32_e32 v35, v2
	v_mov_b32_e32 v36, v2
	v_mov_b32_e32 v37, v2
	v_mov_b32_e32 v38, v2
	v_mov_b32_e32 v39, v2
	v_mov_b32_e32 v40, v2
	v_mov_b32_e32 v41, v2
	v_mov_b32_e32 v42, v2
	v_mov_b32_e32 v43, v2
	v_mov_b32_e32 v44, v2
	v_mov_b32_e32 v45, v2
	v_mov_b32_e32 v46, v2
	v_mov_b32_e32 v47, v2
	v_mov_b32_e32 v48, v2
	v_mov_b32_e32 v49, v2
	v_mov_b32_e32 v50, v2
	v_mov_b32_e32 v51, v2
	v_mov_b32_e32 v52, v2
	v_mov_b32_e32 v53, v2
	v_mov_b32_e32 v54, v2
	v_mov_b32_e32 v55, v2
	v_mov_b32_e32 v86, v2
	v_mov_b32_e32 v87, v2
	v_mov_b32_e32 v88, v2
	v_mov_b32_e32 v89, v2
	v_mov_b32_e32 v90, v2
	v_mov_b32_e32 v91, v2
	v_mov_b32_e32 v92, v2
	v_mov_b32_e32 v93, v2
	v_mov_b32_e32 v94, v2
	v_mov_b32_e32 v95, v2
	v_mov_b32_e32 v96, v2
	v_mov_b32_e32 v97, v2
	v_mov_b32_e32 v98, v2
	v_mov_b32_e32 v99, v2
	v_mov_b32_e32 v100, v2
	v_mov_b32_e32 v101, v2
	v_mov_b32_e32 v102, v2
	v_mov_b32_e32 v103, v2
	v_mov_b32_e32 v104, v2
	v_mov_b32_e32 v105, v2
	v_mov_b32_e32 v138, v2
	v_mov_b32_e32 v139, v2
	v_mov_b32_e32 v140, v2
	v_mov_b32_e32 v141, v2
	v_mov_b32_e32 v142, v2
	v_mov_b32_e32 v143, v2
	v_mov_b32_e32 v144, v2
	v_mov_b32_e32 v145, v2
	v_mov_b32_e32 v146, v2
	v_mov_b32_e32 v147, v2
	v_mov_b32_e32 v148, v2
	v_mov_b32_e32 v149, v2
	v_mov_b32_e32 v150, v2
	v_mov_b32_e32 v151, v2
	v_mov_b32_e32 v152, v2
	v_mov_b32_e32 v153, v2
	v_mov_b32_e32 v154, v2
	v_mov_b32_e32 v155, v2
	v_mov_b32_e32 v156, v2
	v_mov_b32_e32 v157, v2
	v_mov_b32_e32 v158, v2
	v_mov_b32_e32 v159, v2
	v_mov_b32_e32 v160, v2
	v_mov_b32_e32 v161, v2
	s_waitcnt lgkmcnt(0)
	s_barrier
	s_cmp_lg_u32 m0, 0
	s_cbranch_scc1 .Lg1_466
.LBB0_466:
	s_bitcmp1_b32 s4, 0
	s_cselect_b32 s21, 0x12000, 0
	v_or_b32_e32 v184, s21, v206
	v_add_u32_e32 v185, v184, v0
	v_add_u32_e32 v184, v184, v167
	ds_read_b128 v[210:213], v185
	ds_read_b128 v[226:229], v184 offset:32768
	ds_read_b128 v[214:217], v185 offset:2048
	ds_read_b128 v[218:221], v185 offset:4096
	ds_read_b128 v[222:225], v185 offset:6144
	ds_read_b128 v[230:233], v184 offset:34816
	ds_read_b128 v[234:237], v184 offset:36864
	ds_read_b128 v[238:241], v184 offset:38912
	ds_read_b128 v[242:245], v184 offset:40960
	ds_read_b128 v[246:249], v184 offset:43008
	ds_read_b128 v[198:201], v184 offset:45056
	ds_read_b128 v[184:187], v184 offset:47104
	s_add_i32 s10, s4, 1
	s_bitcmp1_b32 s10, 0
	s_cselect_b32 s23, 0x12000, 0
	v_add_u32_e32 v171, s23, v166
	v_xor_b32_e32 v169, 64, v206
	v_add3_u32 v169, s21, v167, v169
	s_waitcnt lgkmcnt(10)
	v_mfma_f32_16x16x32_bf16 v[158:161], v[226:229], v[210:213], v[158:161]
	s_waitcnt lgkmcnt(9)
	v_mfma_f32_16x16x32_bf16 v[94:97], v[226:229], v[214:217], v[94:97]
	s_waitcnt lgkmcnt(8)
	v_mfma_f32_16x16x32_bf16 v[62:65], v[226:229], v[218:221], v[62:65]
	s_waitcnt lgkmcnt(7)
	v_mfma_f32_16x16x32_bf16 v[30:33], v[226:229], v[222:225], v[30:33]
	ds_read_b128 v[226:229], v169 offset:32768
	s_waitcnt lgkmcnt(7)
	v_mfma_f32_16x16x32_bf16 v[154:157], v[230:233], v[210:213], v[154:157]
	v_mfma_f32_16x16x32_bf16 v[90:93], v[230:233], v[214:217], v[90:93]
	v_mfma_f32_16x16x32_bf16 v[58:61], v[230:233], v[218:221], v[58:61]
	v_mfma_f32_16x16x32_bf16 v[26:29], v[230:233], v[222:225], v[26:29]
	ds_read_b128 v[230:233], v169 offset:34816
	s_waitcnt lgkmcnt(7)
	v_mfma_f32_16x16x32_bf16 v[150:153], v[234:237], v[210:213], v[150:153]
	v_mfma_f32_16x16x32_bf16 v[86:89], v[234:237], v[214:217], v[86:89]
	v_mfma_f32_16x16x32_bf16 v[54:57], v[234:237], v[218:221], v[54:57]
	v_mfma_f32_16x16x32_bf16 v[22:25], v[234:237], v[222:225], v[22:25]
	ds_read_b128 v[234:237], v169 offset:36864
	s_waitcnt lgkmcnt(7)
	v_mfma_f32_16x16x32_bf16 v[146:149], v[238:241], v[210:213], v[146:149]
	v_mfma_f32_16x16x32_bf16 v[82:85], v[238:241], v[214:217], v[82:85]
	v_mfma_f32_16x16x32_bf16 v[50:53], v[238:241], v[218:221], v[50:53]
	v_mfma_f32_16x16x32_bf16 v[18:21], v[238:241], v[222:225], v[18:21]
	ds_read_b128 v[238:241], v169 offset:38912
	s_waitcnt lgkmcnt(7)
	v_mfma_f32_16x16x32_bf16 v[142:145], v[242:245], v[210:213], v[142:145]
	v_mfma_f32_16x16x32_bf16 v[78:81], v[242:245], v[214:217], v[78:81]
	v_mfma_f32_16x16x32_bf16 v[46:49], v[242:245], v[218:221], v[46:49]
	v_mfma_f32_16x16x32_bf16 v[14:17], v[242:245], v[222:225], v[14:17]
	ds_read_b128 v[242:245], v169 offset:40960
	s_waitcnt lgkmcnt(7)
	v_mfma_f32_16x16x32_bf16 v[138:141], v[246:249], v[210:213], v[138:141]
	v_mfma_f32_16x16x32_bf16 v[74:77], v[246:249], v[214:217], v[74:77]
	v_mfma_f32_16x16x32_bf16 v[42:45], v[246:249], v[218:221], v[42:45]
	v_mfma_f32_16x16x32_bf16 v[10:13], v[246:249], v[222:225], v[10:13]
	ds_read_b128 v[246:249], v169 offset:43008
	s_waitcnt lgkmcnt(7)
	v_mfma_f32_16x16x32_bf16 v[102:105], v[198:201], v[210:213], v[102:105]
	v_mfma_f32_16x16x32_bf16 v[70:73], v[198:201], v[214:217], v[70:73]
	v_mfma_f32_16x16x32_bf16 v[38:41], v[198:201], v[218:221], v[38:41]
	v_mfma_f32_16x16x32_bf16 v[6:9], v[198:201], v[222:225], v[6:9]
	ds_read_b128 v[198:201], v169 offset:45056
	s_waitcnt lgkmcnt(7)
	v_mfma_f32_16x16x32_bf16 v[98:101], v[184:187], v[210:213], v[98:101]
	v_mfma_f32_16x16x32_bf16 v[66:69], v[184:187], v[214:217], v[66:69]
	v_xor_b32_e32 v169, 64, v206
	v_add3_u32 v169, s21, v0, v169
	ds_read_b128 v[210:213], v169
	ds_read_b128 v[214:217], v169 offset:2048
	v_mfma_f32_16x16x32_bf16 v[34:37], v[184:187], v[218:221], v[34:37]
	ds_read_b128 v[218:221], v169 offset:4096
	v_mfma_f32_16x16x32_bf16 v[2:5], v[184:187], v[222:225], v[2:5]
	ds_read_b128 v[222:225], v169 offset:6144
	v_xor_b32_e32 v169, 64, v206
	v_add3_u32 v169, s21, v167, v169
	ds_read_b128 v[184:187], v169 offset:47104
	s_waitcnt lgkmcnt(4)
	v_mfma_f32_16x16x32_bf16 v[158:161], v[226:229], v[210:213], v[158:161]
	s_waitcnt lgkmcnt(3)
	v_mfma_f32_16x16x32_bf16 v[94:97], v[226:229], v[214:217], v[94:97]
	s_waitcnt lgkmcnt(2)
	v_mfma_f32_16x16x32_bf16 v[62:65], v[226:229], v[218:221], v[62:65]
	s_waitcnt lgkmcnt(1)
	v_mfma_f32_16x16x32_bf16 v[30:33], v[226:229], v[222:225], v[30:33]
	s_waitcnt vmcnt(7)
	ds_write_b128 v171, v[114:117]
	v_mfma_f32_16x16x32_bf16 v[154:157], v[230:233], v[210:213], v[154:157]
	v_mfma_f32_16x16x32_bf16 v[90:93], v[230:233], v[214:217], v[90:93]
	global_load_dwordx4 v[114:117], v168, vcc offset:256
	v_mfma_f32_16x16x32_bf16 v[58:61], v[230:233], v[218:221], v[58:61]
	v_mfma_f32_16x16x32_bf16 v[26:29], v[230:233], v[222:225], v[26:29]
	s_waitcnt vmcnt(7)
	ds_write_b128 v171, v[106:109] offset:8192
	v_mfma_f32_16x16x32_bf16 v[150:153], v[234:237], v[210:213], v[150:153]
	v_mfma_f32_16x16x32_bf16 v[86:89], v[234:237], v[214:217], v[86:89]
	v_add_u32_e32 v106, s34, v168
	global_load_dwordx4 v[106:109], v106, vcc offset:256
	v_mfma_f32_16x16x32_bf16 v[54:57], v[234:237], v[218:221], v[54:57]
	v_mfma_f32_16x16x32_bf16 v[22:25], v[234:237], v[222:225], v[22:25]
	s_waitcnt vmcnt(7)
	ds_write_b128 v171, v[110:113] offset:16384
	v_mfma_f32_16x16x32_bf16 v[146:149], v[238:241], v[210:213], v[146:149]
	v_mfma_f32_16x16x32_bf16 v[82:85], v[238:241], v[214:217], v[82:85]
	v_add_u32_e32 v110, s35, v168
	global_load_dwordx4 v[110:113], v110, vcc offset:256
	v_mfma_f32_16x16x32_bf16 v[50:53], v[238:241], v[218:221], v[50:53]
	v_mfma_f32_16x16x32_bf16 v[18:21], v[238:241], v[222:225], v[18:21]
	s_waitcnt vmcnt(7)
	ds_write_b128 v171, v[126:129] offset:24576
	v_mfma_f32_16x16x32_bf16 v[142:145], v[242:245], v[210:213], v[142:145]
	v_mfma_f32_16x16x32_bf16 v[78:81], v[242:245], v[214:217], v[78:81]
	v_add_u32_e32 v126, s36, v168
	global_load_dwordx4 v[126:129], v126, vcc offset:256
	v_mfma_f32_16x16x32_bf16 v[46:49], v[242:245], v[218:221], v[46:49]
	v_mfma_f32_16x16x32_bf16 v[14:17], v[242:245], v[222:225], v[14:17]
	s_waitcnt vmcnt(7)
	ds_write_b128 v171, v[122:125] offset:32768
	v_mfma_f32_16x16x32_bf16 v[138:141], v[246:249], v[210:213], v[138:141]
	v_mfma_f32_16x16x32_bf16 v[74:77], v[246:249], v[214:217], v[74:77]
	global_load_dwordx4 v[122:125], v170, s[100:101] offset:256
	v_mfma_f32_16x16x32_bf16 v[42:45], v[246:249], v[218:221], v[42:45]
	v_mfma_f32_16x16x32_bf16 v[10:13], v[246:249], v[222:225], v[10:13]
	s_waitcnt vmcnt(7)
	ds_write_b128 v171, v[118:121] offset:40960
	v_mfma_f32_16x16x32_bf16 v[102:105], v[198:201], v[210:213], v[102:105]
	v_mfma_f32_16x16x32_bf16 v[70:73], v[198:201], v[214:217], v[70:73]
	v_add_u32_e32 v118, s34, v170
	global_load_dwordx4 v[118:121], v118, s[100:101] offset:256
	v_mfma_f32_16x16x32_bf16 v[38:41], v[198:201], v[218:221], v[38:41]
	v_mfma_f32_16x16x32_bf16 v[6:9], v[198:201], v[222:225], v[6:9]
	s_waitcnt vmcnt(7)
	ds_write_b128 v171, v[134:137] offset:49152
	s_waitcnt lgkmcnt(7)
	v_mfma_f32_16x16x32_bf16 v[98:101], v[184:187], v[210:213], v[98:101]
	v_mfma_f32_16x16x32_bf16 v[66:69], v[184:187], v[214:217], v[66:69]
	v_add_u32_e32 v134, s35, v170
	global_load_dwordx4 v[134:137], v134, s[100:101] offset:256
	v_mfma_f32_16x16x32_bf16 v[34:37], v[184:187], v[218:221], v[34:37]
	v_mfma_f32_16x16x32_bf16 v[2:5], v[184:187], v[222:225], v[2:5]
	s_waitcnt vmcnt(7)
	ds_write_b128 v171, v[130:133] offset:57344
	v_add_u32_e32 v130, s36, v170
	global_load_dwordx4 v[130:133], v130, s[100:101] offset:256
	v_add_u32_e32 v168, 0x80, v168
	v_add_u32_e32 v170, 0x80, v170
	s_waitcnt lgkmcnt(0)
	s_barrier
	s_cmp_eq_u32 s10, 16
	s_mov_b32 s4, s10
	s_cbranch_scc0 .LBB0_466
	s_branch .Lkdone_466
.Lg1_466:
	v_add_u32_e32 v171, 0x12000, v166
	s_waitcnt vmcnt(7)
	ds_write_b128 v171, v[114:117]
	global_load_dwordx4 v[114:117], v168, vcc offset:256
	s_waitcnt vmcnt(7)
	ds_write_b128 v171, v[106:109] offset:8192
	v_add_u32_e32 v106, s34, v168
	global_load_dwordx4 v[106:109], v106, vcc offset:256
	s_waitcnt vmcnt(7)
	ds_write_b128 v171, v[110:113] offset:16384
	v_add_u32_e32 v110, s35, v168
	global_load_dwordx4 v[110:113], v110, vcc offset:256
	s_waitcnt vmcnt(7)
	ds_write_b128 v171, v[126:129] offset:24576
	v_add_u32_e32 v126, s36, v168
	global_load_dwordx4 v[126:129], v126, vcc offset:256
	s_waitcnt vmcnt(7)
	ds_write_b128 v171, v[122:125] offset:32768
	global_load_dwordx4 v[122:125], v170, s[100:101] offset:256
	s_waitcnt vmcnt(7)
	ds_write_b128 v171, v[118:121] offset:40960
	v_add_u32_e32 v118, s34, v170
	global_load_dwordx4 v[118:121], v118, s[100:101] offset:256
	s_waitcnt vmcnt(7)
	ds_write_b128 v171, v[134:137] offset:49152
	v_add_u32_e32 v134, s35, v170
	global_load_dwordx4 v[134:137], v134, s[100:101] offset:256
	s_waitcnt vmcnt(7)
	ds_write_b128 v171, v[130:133] offset:57344
	v_add_u32_e32 v130, s36, v170
	global_load_dwordx4 v[130:133], v130, s[100:101] offset:256
	v_add_u32_e32 v168, 0x80, v168
	v_add_u32_e32 v170, 0x80, v170
.Lg1loop_466:
	s_bitcmp1_b32 s4, 0
	s_cselect_b32 s21, 0x12000, 0
	v_or_b32_e32 v184, s21, v206
	v_add_u32_e32 v185, v184, v0
	v_add_u32_e32 v184, v184, v167
	ds_read_b128 v[210:213], v185
	ds_read_b128 v[226:229], v184 offset:32768
	ds_read_b128 v[214:217], v185 offset:2048
	ds_read_b128 v[218:221], v185 offset:4096
	ds_read_b128 v[222:225], v185 offset:6144
	ds_read_b128 v[230:233], v184 offset:34816
	ds_read_b128 v[234:237], v184 offset:36864
	ds_read_b128 v[238:241], v184 offset:38912
	ds_read_b128 v[242:245], v184 offset:40960
	ds_read_b128 v[246:249], v184 offset:43008
	ds_read_b128 v[198:201], v184 offset:45056
	ds_read_b128 v[184:187], v184 offset:47104
	s_add_i32 s10, s4, 1
	s_bitcmp1_b32 s10, 0
	s_cselect_b32 s23, 0x12000, 0
	v_add_u32_e32 v171, s21, v166
	v_xor_b32_e32 v169, 64, v206
	v_add3_u32 v169, s21, v167, v169
	s_waitcnt lgkmcnt(10)
	v_mfma_f32_16x16x32_bf16 v[158:161], v[226:229], v[210:213], v[158:161]
	s_waitcnt lgkmcnt(9)
	v_mfma_f32_16x16x32_bf16 v[94:97], v[226:229], v[214:217], v[94:97]
	s_waitcnt lgkmcnt(8)
	v_mfma_f32_16x16x32_bf16 v[62:65], v[226:229], v[218:221], v[62:65]
	s_waitcnt lgkmcnt(7)
	v_mfma_f32_16x16x32_bf16 v[30:33], v[226:229], v[222:225], v[30:33]
	ds_read_b128 v[226:229], v169 offset:32768
	s_waitcnt lgkmcnt(7)
	v_mfma_f32_16x16x32_bf16 v[154:157], v[230:233], v[210:213], v[154:157]
	v_mfma_f32_16x16x32_bf16 v[90:93], v[230:233], v[214:217], v[90:93]
	v_mfma_f32_16x16x32_bf16 v[58:61], v[230:233], v[218:221], v[58:61]
	v_mfma_f32_16x16x32_bf16 v[26:29], v[230:233], v[222:225], v[26:29]
	ds_read_b128 v[230:233], v169 offset:34816
	s_waitcnt lgkmcnt(7)
	v_mfma_f32_16x16x32_bf16 v[150:153], v[234:237], v[210:213], v[150:153]
	v_mfma_f32_16x16x32_bf16 v[86:89], v[234:237], v[214:217], v[86:89]
	v_mfma_f32_16x16x32_bf16 v[54:57], v[234:237], v[218:221], v[54:57]
	v_mfma_f32_16x16x32_bf16 v[22:25], v[234:237], v[222:225], v[22:25]
	ds_read_b128 v[234:237], v169 offset:36864
	s_waitcnt lgkmcnt(7)
	v_mfma_f32_16x16x32_bf16 v[146:149], v[238:241], v[210:213], v[146:149]
	v_mfma_f32_16x16x32_bf16 v[82:85], v[238:241], v[214:217], v[82:85]
	v_mfma_f32_16x16x32_bf16 v[50:53], v[238:241], v[218:221], v[50:53]
	v_mfma_f32_16x16x32_bf16 v[18:21], v[238:241], v[222:225], v[18:21]
	ds_read_b128 v[238:241], v169 offset:38912
	s_waitcnt lgkmcnt(7)
	v_mfma_f32_16x16x32_bf16 v[142:145], v[242:245], v[210:213], v[142:145]
	v_mfma_f32_16x16x32_bf16 v[78:81], v[242:245], v[214:217], v[78:81]
	v_mfma_f32_16x16x32_bf16 v[46:49], v[242:245], v[218:221], v[46:49]
	v_mfma_f32_16x16x32_bf16 v[14:17], v[242:245], v[222:225], v[14:17]
	ds_read_b128 v[242:245], v169 offset:40960
	s_waitcnt lgkmcnt(7)
	v_mfma_f32_16x16x32_bf16 v[138:141], v[246:249], v[210:213], v[138:141]
	v_mfma_f32_16x16x32_bf16 v[74:77], v[246:249], v[214:217], v[74:77]
	v_mfma_f32_16x16x32_bf16 v[42:45], v[246:249], v[218:221], v[42:45]
	v_mfma_f32_16x16x32_bf16 v[10:13], v[246:249], v[222:225], v[10:13]
	ds_read_b128 v[246:249], v169 offset:43008
	s_waitcnt lgkmcnt(7)
	v_mfma_f32_16x16x32_bf16 v[102:105], v[198:201], v[210:213], v[102:105]
	v_mfma_f32_16x16x32_bf16 v[70:73], v[198:201], v[214:217], v[70:73]
	v_mfma_f32_16x16x32_bf16 v[38:41], v[198:201], v[218:221], v[38:41]
	v_mfma_f32_16x16x32_bf16 v[6:9], v[198:201], v[222:225], v[6:9]
	ds_read_b128 v[198:201], v169 offset:45056
	s_waitcnt lgkmcnt(7)
	v_mfma_f32_16x16x32_bf16 v[98:101], v[184:187], v[210:213], v[98:101]
	v_mfma_f32_16x16x32_bf16 v[66:69], v[184:187], v[214:217], v[66:69]
	v_xor_b32_e32 v169, 64, v206
	v_add3_u32 v169, s21, v0, v169
	ds_read_b128 v[210:213], v169
	ds_read_b128 v[214:217], v169 offset:2048
	v_mfma_f32_16x16x32_bf16 v[34:37], v[184:187], v[218:221], v[34:37]
	ds_read_b128 v[218:221], v169 offset:4096
	v_mfma_f32_16x16x32_bf16 v[2:5], v[184:187], v[222:225], v[2:5]
	ds_read_b128 v[222:225], v169 offset:6144
	v_xor_b32_e32 v169, 64, v206
	v_add3_u32 v169, s21, v167, v169
	ds_read_b128 v[184:187], v169 offset:47104
	s_waitcnt lgkmcnt(0)
	s_barrier
	s_waitcnt lgkmcnt(4)
	v_mfma_f32_16x16x32_bf16 v[158:161], v[226:229], v[210:213], v[158:161]
	s_waitcnt lgkmcnt(3)
	v_mfma_f32_16x16x32_bf16 v[94:97], v[226:229], v[214:217], v[94:97]
	s_waitcnt lgkmcnt(2)
	v_mfma_f32_16x16x32_bf16 v[62:65], v[226:229], v[218:221], v[62:65]
	s_waitcnt lgkmcnt(1)
	v_mfma_f32_16x16x32_bf16 v[30:33], v[226:229], v[222:225], v[30:33]
	s_waitcnt vmcnt(7)
	ds_write_b128 v171, v[114:117]
	v_mfma_f32_16x16x32_bf16 v[154:157], v[230:233], v[210:213], v[154:157]
	v_mfma_f32_16x16x32_bf16 v[90:93], v[230:233], v[214:217], v[90:93]
	global_load_dwordx4 v[114:117], v168, vcc offset:256
	v_mfma_f32_16x16x32_bf16 v[58:61], v[230:233], v[218:221], v[58:61]
	v_mfma_f32_16x16x32_bf16 v[26:29], v[230:233], v[222:225], v[26:29]
	s_waitcnt vmcnt(7)
	ds_write_b128 v171, v[106:109] offset:8192
	v_mfma_f32_16x16x32_bf16 v[150:153], v[234:237], v[210:213], v[150:153]
	v_mfma_f32_16x16x32_bf16 v[86:89], v[234:237], v[214:217], v[86:89]
	v_add_u32_e32 v106, s34, v168
	global_load_dwordx4 v[106:109], v106, vcc offset:256
	v_mfma_f32_16x16x32_bf16 v[54:57], v[234:237], v[218:221], v[54:57]
	v_mfma_f32_16x16x32_bf16 v[22:25], v[234:237], v[222:225], v[22:25]
	s_waitcnt vmcnt(7)
	ds_write_b128 v171, v[110:113] offset:16384
	v_mfma_f32_16x16x32_bf16 v[146:149], v[238:241], v[210:213], v[146:149]
	v_mfma_f32_16x16x32_bf16 v[82:85], v[238:241], v[214:217], v[82:85]
	v_add_u32_e32 v110, s35, v168
	global_load_dwordx4 v[110:113], v110, vcc offset:256
	v_mfma_f32_16x16x32_bf16 v[50:53], v[238:241], v[218:221], v[50:53]
	v_mfma_f32_16x16x32_bf16 v[18:21], v[238:241], v[222:225], v[18:21]
	s_waitcnt vmcnt(7)
	ds_write_b128 v171, v[126:129] offset:24576
	v_mfma_f32_16x16x32_bf16 v[142:145], v[242:245], v[210:213], v[142:145]
	v_mfma_f32_16x16x32_bf16 v[78:81], v[242:245], v[214:217], v[78:81]
	v_add_u32_e32 v126, s36, v168
	global_load_dwordx4 v[126:129], v126, vcc offset:256
	v_mfma_f32_16x16x32_bf16 v[46:49], v[242:245], v[218:221], v[46:49]
	v_mfma_f32_16x16x32_bf16 v[14:17], v[242:245], v[222:225], v[14:17]
	s_waitcnt vmcnt(7)
	ds_write_b128 v171, v[122:125] offset:32768
	v_mfma_f32_16x16x32_bf16 v[138:141], v[246:249], v[210:213], v[138:141]
	v_mfma_f32_16x16x32_bf16 v[74:77], v[246:249], v[214:217], v[74:77]
	global_load_dwordx4 v[122:125], v170, s[100:101] offset:256
	v_mfma_f32_16x16x32_bf16 v[42:45], v[246:249], v[218:221], v[42:45]
	v_mfma_f32_16x16x32_bf16 v[10:13], v[246:249], v[222:225], v[10:13]
	s_waitcnt vmcnt(7)
	ds_write_b128 v171, v[118:121] offset:40960
	v_mfma_f32_16x16x32_bf16 v[102:105], v[198:201], v[210:213], v[102:105]
	v_mfma_f32_16x16x32_bf16 v[70:73], v[198:201], v[214:217], v[70:73]
	v_add_u32_e32 v118, s34, v170
	global_load_dwordx4 v[118:121], v118, s[100:101] offset:256
	v_mfma_f32_16x16x32_bf16 v[38:41], v[198:201], v[218:221], v[38:41]
	v_mfma_f32_16x16x32_bf16 v[6:9], v[198:201], v[222:225], v[6:9]
	s_waitcnt vmcnt(7)
	ds_write_b128 v171, v[134:137] offset:49152
	s_waitcnt lgkmcnt(7)
	v_mfma_f32_16x16x32_bf16 v[98:101], v[184:187], v[210:213], v[98:101]
	v_mfma_f32_16x16x32_bf16 v[66:69], v[184:187], v[214:217], v[66:69]
	v_add_u32_e32 v134, s35, v170
	global_load_dwordx4 v[134:137], v134, s[100:101] offset:256
	v_mfma_f32_16x16x32_bf16 v[34:37], v[184:187], v[218:221], v[34:37]
	v_mfma_f32_16x16x32_bf16 v[2:5], v[184:187], v[222:225], v[2:5]
	s_waitcnt vmcnt(7)
	ds_write_b128 v171, v[130:133] offset:57344
	v_add_u32_e32 v130, s36, v170
	global_load_dwordx4 v[130:133], v130, s[100:101] offset:256
	v_add_u32_e32 v168, 0x80, v168
	v_add_u32_e32 v170, 0x80, v170
	s_cmp_eq_u32 s10, 16
	s_mov_b32 s4, s10
	s_cbranch_scc0 .Lg1loop_466
	s_waitcnt lgkmcnt(0)
.Lkdone_466:
	s_waitcnt vmcnt(6)
	v_mul_f32_e32 v109, 0xbfb8aa3b, v158
	v_exp_f32_e32 v109, v109
	s_waitcnt vmcnt(5)
	v_mul_f32_e32 v111, 0xbfb8aa3b, v159
	v_exp_f32_e32 v111, v111
	v_mul_f32_e32 v115, 0xbfb8aa3b, v161
	v_add_f32_e32 v109, 1.0, v109
	v_rcp_f32_e32 v114, v109
	v_add_f32_e32 v109, 1.0, v111
	v_mul_f32_e32 v111, 0xbfb8aa3b, v160
	v_exp_f32_e32 v111, v111
	v_exp_f32_e32 v117, v115
	v_rcp_f32_e32 v116, v109
	s_waitcnt vmcnt(2)
	v_mov_b32_e32 v118, v158
	v_add_f32_e32 v109, 1.0, v111
	v_rcp_f32_e32 v115, v109
	v_add_f32_e32 v109, 1.0, v117
	v_rcp_f32_e32 v117, v109
	v_mov_b32_e32 v119, v160
	v_pk_mul_f32 v[114:115], v[118:119], v[114:115]
	v_mov_b32_e32 v118, v154
	v_mov_b32_e32 v119, v156
	v_mov_b32_e32 v160, v159
	v_pk_mul_f32 v[114:115], v[118:119], v[114:115]
	v_pk_mul_f32 v[116:117], v[160:161], v[116:117]
	v_mov_b32_e32 v156, v155
	v_pk_mul_f32 v[116:117], v[156:157], v[116:117]
	v_and_b32_sdwa v111, v115, v177 dst_sel:DWORD dst_unused:UNUSED_PAD src0_sel:WORD_1 src1_sel:DWORD
	v_and_b32_sdwa v118, v114, v177 dst_sel:DWORD dst_unused:UNUSED_PAD src0_sel:WORD_1 src1_sel:DWORD
	v_add3_u32 v111, v115, v111, s28
	v_and_b32_sdwa v115, v117, v177 dst_sel:DWORD dst_unused:UNUSED_PAD src0_sel:WORD_1 src1_sel:DWORD
	v_add3_u32 v114, v114, v118, s28
	v_and_b32_sdwa v118, v116, v177 dst_sel:DWORD dst_unused:UNUSED_PAD src0_sel:WORD_1 src1_sel:DWORD
	v_add3_u32 v115, v117, v115, s28
	v_or_b32_e32 v106, s7, v207
	v_add3_u32 v116, v116, v118, s28
	v_and_b32_e32 v115, 0xffff0000, v115
	v_ashrrev_i32_e32 v106, 1, v106
	v_and_b32_e32 v116, 0xffff0000, v116
	v_or_b32_sdwa v115, v115, v111 dst_sel:DWORD dst_unused:UNUSED_PAD src0_sel:DWORD src1_sel:WORD_1
	v_mul_f32_e32 v111, 0xbfb8aa3b, v150
	v_or_b32_e32 v108, v106, v208
	v_or_b32_sdwa v114, v116, v114 dst_sel:DWORD dst_unused:UNUSED_PAD src0_sel:DWORD src1_sel:WORD_1
	v_exp_f32_e32 v111, v111
	v_mul_f32_e32 v116, 0xbfb8aa3b, v151
	v_add_u32_e32 v110, s6, v205
	v_mov_b64_e32 v[106:107], s[14:15]
	v_ashrrev_i32_e32 v109, 31, v108
	v_exp_f32_e32 v116, v116
	v_mad_i64_i32 v[112:113], s[6:7], v110, s52, v[106:107]
	v_lshlrev_b64 v[108:109], 1, v[108:109]
	v_lshl_add_u64 v[112:113], v[112:113], 0, v[108:109]
	s_waitcnt vmcnt(0)
	global_store_dwordx2 v[112:113], v[114:115], off
	v_add_f32_e32 v111, 1.0, v111
	v_mul_f32_e32 v115, 0xbfb8aa3b, v152
	v_rcp_f32_e32 v114, v111
	v_add_f32_e32 v111, 1.0, v116
	v_exp_f32_e32 v115, v115
	v_mul_f32_e32 v116, 0xbfb8aa3b, v153
	v_exp_f32_e32 v117, v116
	v_rcp_f32_e32 v116, v111
	v_add_f32_e32 v111, 1.0, v115
	v_rcp_f32_e32 v115, v111
	v_add_f32_e32 v111, 1.0, v117
	v_rcp_f32_e32 v117, v111
	v_mov_b32_e32 v118, v150
	v_mov_b32_e32 v119, v152
	v_pk_mul_f32 v[114:115], v[118:119], v[114:115]
	v_mov_b32_e32 v118, v146
	v_mov_b32_e32 v119, v148
	v_mov_b32_e32 v152, v151
	v_pk_mul_f32 v[114:115], v[118:119], v[114:115]
	v_pk_mul_f32 v[116:117], v[152:153], v[116:117]
	v_mov_b32_e32 v148, v147
	v_pk_mul_f32 v[116:117], v[148:149], v[116:117]
	v_and_b32_sdwa v111, v115, v177 dst_sel:DWORD dst_unused:UNUSED_PAD src0_sel:WORD_1 src1_sel:DWORD
	v_and_b32_sdwa v118, v114, v177 dst_sel:DWORD dst_unused:UNUSED_PAD src0_sel:WORD_1 src1_sel:DWORD
	v_add3_u32 v111, v115, v111, s28
	v_and_b32_sdwa v115, v117, v177 dst_sel:DWORD dst_unused:UNUSED_PAD src0_sel:WORD_1 src1_sel:DWORD
	v_add3_u32 v114, v114, v118, s28
	v_and_b32_sdwa v118, v116, v177 dst_sel:DWORD dst_unused:UNUSED_PAD src0_sel:WORD_1 src1_sel:DWORD
	v_add3_u32 v115, v117, v115, s28
	v_add3_u32 v116, v116, v118, s28
	v_and_b32_e32 v115, 0xffff0000, v115
	v_and_b32_e32 v116, 0xffff0000, v116
	v_or_b32_sdwa v115, v115, v111 dst_sel:DWORD dst_unused:UNUSED_PAD src0_sel:DWORD src1_sel:WORD_1
	v_mul_f32_e32 v111, 0xbfb8aa3b, v142
	v_or_b32_sdwa v114, v116, v114 dst_sel:DWORD dst_unused:UNUSED_PAD src0_sel:DWORD src1_sel:WORD_1
	v_exp_f32_e32 v111, v111
	v_mul_f32_e32 v116, 0xbfb8aa3b, v143
	v_exp_f32_e32 v116, v116
	global_store_dwordx2 v[112:113], v[114:115], off offset:32
	v_add_f32_e32 v111, 1.0, v111
	v_mul_f32_e32 v115, 0xbfb8aa3b, v144
	v_rcp_f32_e32 v114, v111
	v_add_f32_e32 v111, 1.0, v116
	v_exp_f32_e32 v115, v115
	v_mul_f32_e32 v116, 0xbfb8aa3b, v145
	v_exp_f32_e32 v117, v116
	v_rcp_f32_e32 v116, v111
	v_add_f32_e32 v111, 1.0, v115
	v_rcp_f32_e32 v115, v111
	v_add_f32_e32 v111, 1.0, v117
	v_rcp_f32_e32 v117, v111
	v_mov_b32_e32 v118, v142
	v_mov_b32_e32 v119, v144
	v_pk_mul_f32 v[114:115], v[118:119], v[114:115]
	v_mov_b32_e32 v118, v138
	v_mov_b32_e32 v119, v140
	v_mov_b32_e32 v144, v143
	v_pk_mul_f32 v[114:115], v[118:119], v[114:115]
	v_pk_mul_f32 v[116:117], v[144:145], v[116:117]
	v_mov_b32_e32 v140, v139
	v_pk_mul_f32 v[116:117], v[140:141], v[116:117]
	v_and_b32_sdwa v111, v115, v177 dst_sel:DWORD dst_unused:UNUSED_PAD src0_sel:WORD_1 src1_sel:DWORD
	v_and_b32_sdwa v118, v114, v177 dst_sel:DWORD dst_unused:UNUSED_PAD src0_sel:WORD_1 src1_sel:DWORD
	v_add3_u32 v111, v115, v111, s28
	v_and_b32_sdwa v115, v117, v177 dst_sel:DWORD dst_unused:UNUSED_PAD src0_sel:WORD_1 src1_sel:DWORD
	v_add3_u32 v114, v114, v118, s28
	v_and_b32_sdwa v118, v116, v177 dst_sel:DWORD dst_unused:UNUSED_PAD src0_sel:WORD_1 src1_sel:DWORD
	v_add3_u32 v115, v117, v115, s28
	v_add3_u32 v116, v116, v118, s28
	v_and_b32_e32 v115, 0xffff0000, v115
	v_and_b32_e32 v116, 0xffff0000, v116
	v_or_b32_sdwa v115, v115, v111 dst_sel:DWORD dst_unused:UNUSED_PAD src0_sel:DWORD src1_sel:WORD_1
	v_mul_f32_e32 v111, 0xbfb8aa3b, v102
	v_or_b32_sdwa v114, v116, v114 dst_sel:DWORD dst_unused:UNUSED_PAD src0_sel:DWORD src1_sel:WORD_1
	v_exp_f32_e32 v111, v111
	v_mul_f32_e32 v116, 0xbfb8aa3b, v103
	v_exp_f32_e32 v116, v116
	global_store_dwordx2 v[112:113], v[114:115], off offset:64
	v_add_f32_e32 v111, 1.0, v111
	v_mul_f32_e32 v115, 0xbfb8aa3b, v104
	v_rcp_f32_e32 v114, v111
	v_add_f32_e32 v111, 1.0, v116
	v_exp_f32_e32 v115, v115
	v_mul_f32_e32 v116, 0xbfb8aa3b, v105
	v_exp_f32_e32 v117, v116
	v_rcp_f32_e32 v116, v111
	v_add_f32_e32 v111, 1.0, v115
	v_rcp_f32_e32 v115, v111
	v_add_f32_e32 v111, 1.0, v117
	v_rcp_f32_e32 v117, v111
	v_mov_b32_e32 v118, v102
	v_mov_b32_e32 v119, v104
	v_mov_b32_e32 v104, v103
	v_pk_mul_f32 v[114:115], v[118:119], v[114:115]
	v_mov_b32_e32 v119, v100
	v_pk_mul_f32 v[102:103], v[104:105], v[116:117]
	v_mov_b32_e32 v100, v99
	v_mov_b32_e32 v118, v98
	v_pk_mul_f32 v[98:99], v[100:101], v[102:103]
	v_pk_mul_f32 v[114:115], v[118:119], v[114:115]
	v_and_b32_sdwa v102, v99, v177 dst_sel:DWORD dst_unused:UNUSED_PAD src0_sel:WORD_1 src1_sel:DWORD
	v_and_b32_sdwa v103, v98, v177 dst_sel:DWORD dst_unused:UNUSED_PAD src0_sel:WORD_1 src1_sel:DWORD
	v_and_b32_sdwa v100, v115, v177 dst_sel:DWORD dst_unused:UNUSED_PAD src0_sel:WORD_1 src1_sel:DWORD
	v_and_b32_sdwa v101, v114, v177 dst_sel:DWORD dst_unused:UNUSED_PAD src0_sel:WORD_1 src1_sel:DWORD
	v_add3_u32 v99, v99, v102, s28
	v_add3_u32 v98, v98, v103, s28
	v_add3_u32 v101, v114, v101, s28
	v_add3_u32 v100, v115, v100, s28
	v_and_b32_e32 v99, 0xffff0000, v99
	v_and_b32_e32 v98, 0xffff0000, v98
	v_or_b32_sdwa v99, v99, v100 dst_sel:DWORD dst_unused:UNUSED_PAD src0_sel:DWORD src1_sel:WORD_1
	v_or_b32_sdwa v98, v98, v101 dst_sel:DWORD dst_unused:UNUSED_PAD src0_sel:DWORD src1_sel:WORD_1
	global_store_dwordx2 v[112:113], v[98:99], off offset:96
	v_mul_f32_e32 v99, 0xbfb8aa3b, v94
	v_exp_f32_e32 v100, v99
	v_mul_f32_e32 v99, 0xbfb8aa3b, v95
	v_mul_f32_e32 v102, 0xbfb8aa3b, v96
	v_exp_f32_e32 v101, v99
	v_exp_f32_e32 v103, v102
	v_mul_f32_e32 v102, 0xbfb8aa3b, v97
	v_exp_f32_e32 v104, v102
	v_add_f32_e32 v101, 1.0, v101
	v_add_f32_e32 v100, 1.0, v100
	v_rcp_f32_e32 v102, v101
	v_add_f32_e32 v101, 1.0, v103
	v_add_f32_e32 v103, 1.0, v104
	v_rcp_f32_e32 v100, v100
	v_rcp_f32_e32 v101, v101
	v_rcp_f32_e32 v103, v103
	v_mov_b32_e32 v104, v94
	v_mov_b32_e32 v105, v96
	v_mov_b32_e32 v96, v95
	v_pk_mul_f32 v[100:101], v[104:105], v[100:101]
	v_mov_b32_e32 v105, v92
	v_pk_mul_f32 v[94:95], v[96:97], v[102:103]
	v_mov_b32_e32 v92, v91
	v_mov_b32_e32 v104, v90
	v_pk_mul_f32 v[90:91], v[92:93], v[94:95]
	v_pk_mul_f32 v[100:101], v[104:105], v[100:101]
	v_and_b32_sdwa v94, v91, v177 dst_sel:DWORD dst_unused:UNUSED_PAD src0_sel:WORD_1 src1_sel:DWORD
	v_and_b32_sdwa v92, v101, v177 dst_sel:DWORD dst_unused:UNUSED_PAD src0_sel:WORD_1 src1_sel:DWORD
	v_and_b32_sdwa v95, v90, v177 dst_sel:DWORD dst_unused:UNUSED_PAD src0_sel:WORD_1 src1_sel:DWORD
	v_add3_u32 v91, v91, v94, s28
	v_and_b32_sdwa v93, v100, v177 dst_sel:DWORD dst_unused:UNUSED_PAD src0_sel:WORD_1 src1_sel:DWORD
	v_add3_u32 v92, v101, v92, s28
	v_add3_u32 v90, v90, v95, s28
	v_and_b32_e32 v91, 0xffff0000, v91
	v_add3_u32 v93, v100, v93, s28
	v_and_b32_e32 v90, 0xffff0000, v90
	v_or_b32_sdwa v91, v91, v92 dst_sel:DWORD dst_unused:UNUSED_PAD src0_sel:DWORD src1_sel:WORD_1
	v_mul_f32_e32 v92, 0xbfb8aa3b, v86
	v_or_b32_sdwa v90, v90, v93 dst_sel:DWORD dst_unused:UNUSED_PAD src0_sel:DWORD src1_sel:WORD_1
	v_exp_f32_e32 v92, v92
	v_mul_f32_e32 v93, 0xbfb8aa3b, v87
	v_or_b32_e32 v98, 16, v110
	v_exp_f32_e32 v93, v93
	v_mad_i64_i32 v[98:99], s[6:7], v98, s52, v[106:107]
	v_lshl_add_u64 v[98:99], v[98:99], 0, v[108:109]
	global_store_dwordx2 v[98:99], v[90:91], off
	v_add_f32_e32 v90, 1.0, v92
	v_mul_f32_e32 v92, 0xbfb8aa3b, v88
	v_add_f32_e32 v91, 1.0, v93
	v_exp_f32_e32 v93, v92
	v_mul_f32_e32 v92, 0xbfb8aa3b, v89
	v_exp_f32_e32 v94, v92
	v_rcp_f32_e32 v92, v91
	v_add_f32_e32 v91, 1.0, v93
	v_rcp_f32_e32 v90, v90
	v_add_f32_e32 v93, 1.0, v94
	v_rcp_f32_e32 v91, v91
	v_rcp_f32_e32 v93, v93
	v_mov_b32_e32 v94, v86
	v_mov_b32_e32 v95, v88
	v_mov_b32_e32 v88, v87
	v_pk_mul_f32 v[90:91], v[94:95], v[90:91]
	v_mov_b32_e32 v95, v84
	v_pk_mul_f32 v[86:87], v[88:89], v[92:93]
	v_mov_b32_e32 v84, v83
	v_mov_b32_e32 v94, v82
	v_pk_mul_f32 v[82:83], v[84:85], v[86:87]
	v_pk_mul_f32 v[90:91], v[94:95], v[90:91]
	v_and_b32_sdwa v86, v83, v177 dst_sel:DWORD dst_unused:UNUSED_PAD src0_sel:WORD_1 src1_sel:DWORD
	v_and_b32_sdwa v84, v91, v177 dst_sel:DWORD dst_unused:UNUSED_PAD src0_sel:WORD_1 src1_sel:DWORD
	v_and_b32_sdwa v87, v82, v177 dst_sel:DWORD dst_unused:UNUSED_PAD src0_sel:WORD_1 src1_sel:DWORD
	v_add3_u32 v83, v83, v86, s28
	v_and_b32_sdwa v85, v90, v177 dst_sel:DWORD dst_unused:UNUSED_PAD src0_sel:WORD_1 src1_sel:DWORD
	v_add3_u32 v84, v91, v84, s28
	v_add3_u32 v82, v82, v87, s28
	v_and_b32_e32 v83, 0xffff0000, v83
	v_add3_u32 v85, v90, v85, s28
	v_and_b32_e32 v82, 0xffff0000, v82
	v_or_b32_sdwa v83, v83, v84 dst_sel:DWORD dst_unused:UNUSED_PAD src0_sel:DWORD src1_sel:WORD_1
	v_mul_f32_e32 v84, 0xbfb8aa3b, v78
	v_or_b32_sdwa v82, v82, v85 dst_sel:DWORD dst_unused:UNUSED_PAD src0_sel:DWORD src1_sel:WORD_1
	v_exp_f32_e32 v84, v84
	v_mul_f32_e32 v85, 0xbfb8aa3b, v79
	v_exp_f32_e32 v85, v85
	global_store_dwordx2 v[98:99], v[82:83], off offset:32
	v_add_f32_e32 v82, 1.0, v84
	v_mul_f32_e32 v84, 0xbfb8aa3b, v80
	v_add_f32_e32 v83, 1.0, v85
	v_exp_f32_e32 v85, v84
	v_mul_f32_e32 v84, 0xbfb8aa3b, v81
	v_exp_f32_e32 v86, v84
	v_rcp_f32_e32 v84, v83
	v_add_f32_e32 v83, 1.0, v85
	v_rcp_f32_e32 v82, v82
	v_add_f32_e32 v85, 1.0, v86
	v_rcp_f32_e32 v83, v83
	v_rcp_f32_e32 v85, v85
	v_mov_b32_e32 v86, v78
	v_mov_b32_e32 v87, v80
	v_mov_b32_e32 v80, v79
	v_pk_mul_f32 v[82:83], v[86:87], v[82:83]
	v_mov_b32_e32 v87, v76
	v_pk_mul_f32 v[78:79], v[80:81], v[84:85]
	v_mov_b32_e32 v76, v75
	v_mov_b32_e32 v86, v74
	v_pk_mul_f32 v[74:75], v[76:77], v[78:79]
	v_pk_mul_f32 v[82:83], v[86:87], v[82:83]
	v_and_b32_sdwa v78, v75, v177 dst_sel:DWORD dst_unused:UNUSED_PAD src0_sel:WORD_1 src1_sel:DWORD
	v_and_b32_sdwa v76, v83, v177 dst_sel:DWORD dst_unused:UNUSED_PAD src0_sel:WORD_1 src1_sel:DWORD
	v_and_b32_sdwa v79, v74, v177 dst_sel:DWORD dst_unused:UNUSED_PAD src0_sel:WORD_1 src1_sel:DWORD
	v_add3_u32 v75, v75, v78, s28
	v_and_b32_sdwa v77, v82, v177 dst_sel:DWORD dst_unused:UNUSED_PAD src0_sel:WORD_1 src1_sel:DWORD
	v_add3_u32 v76, v83, v76, s28
	v_add3_u32 v74, v74, v79, s28
	v_and_b32_e32 v75, 0xffff0000, v75
	v_add3_u32 v77, v82, v77, s28
	v_and_b32_e32 v74, 0xffff0000, v74
	v_or_b32_sdwa v75, v75, v76 dst_sel:DWORD dst_unused:UNUSED_PAD src0_sel:DWORD src1_sel:WORD_1
	v_mul_f32_e32 v76, 0xbfb8aa3b, v70
	v_or_b32_sdwa v74, v74, v77 dst_sel:DWORD dst_unused:UNUSED_PAD src0_sel:DWORD src1_sel:WORD_1
	v_exp_f32_e32 v76, v76
	v_mul_f32_e32 v77, 0xbfb8aa3b, v71
	v_exp_f32_e32 v77, v77
	global_store_dwordx2 v[98:99], v[74:75], off offset:64
	v_add_f32_e32 v74, 1.0, v76
	v_mul_f32_e32 v76, 0xbfb8aa3b, v72
	v_add_f32_e32 v75, 1.0, v77
	v_exp_f32_e32 v77, v76
	v_mul_f32_e32 v76, 0xbfb8aa3b, v73
	v_exp_f32_e32 v78, v76
	v_rcp_f32_e32 v76, v75
	v_add_f32_e32 v75, 1.0, v77
	v_rcp_f32_e32 v74, v74
	v_add_f32_e32 v77, 1.0, v78
	v_rcp_f32_e32 v75, v75
	v_rcp_f32_e32 v77, v77
	v_mov_b32_e32 v78, v70
	v_mov_b32_e32 v79, v72
	v_mov_b32_e32 v72, v71
	v_pk_mul_f32 v[74:75], v[78:79], v[74:75]
	v_mov_b32_e32 v79, v68
	v_pk_mul_f32 v[70:71], v[72:73], v[76:77]
	v_mov_b32_e32 v68, v67
	v_mov_b32_e32 v78, v66
	v_pk_mul_f32 v[66:67], v[68:69], v[70:71]
	v_pk_mul_f32 v[74:75], v[78:79], v[74:75]
	v_and_b32_sdwa v70, v67, v177 dst_sel:DWORD dst_unused:UNUSED_PAD src0_sel:WORD_1 src1_sel:DWORD
	v_and_b32_sdwa v71, v66, v177 dst_sel:DWORD dst_unused:UNUSED_PAD src0_sel:WORD_1 src1_sel:DWORD
	v_and_b32_sdwa v68, v75, v177 dst_sel:DWORD dst_unused:UNUSED_PAD src0_sel:WORD_1 src1_sel:DWORD
	v_and_b32_sdwa v69, v74, v177 dst_sel:DWORD dst_unused:UNUSED_PAD src0_sel:WORD_1 src1_sel:DWORD
	v_add3_u32 v67, v67, v70, s28
	v_add3_u32 v66, v66, v71, s28
	v_add3_u32 v69, v74, v69, s28
	v_add3_u32 v68, v75, v68, s28
	v_and_b32_e32 v67, 0xffff0000, v67
	v_and_b32_e32 v66, 0xffff0000, v66
	v_or_b32_sdwa v67, v67, v68 dst_sel:DWORD dst_unused:UNUSED_PAD src0_sel:DWORD src1_sel:WORD_1
	v_or_b32_sdwa v66, v66, v69 dst_sel:DWORD dst_unused:UNUSED_PAD src0_sel:DWORD src1_sel:WORD_1
	global_store_dwordx2 v[98:99], v[66:67], off offset:96
	v_mul_f32_e32 v67, 0xbfb8aa3b, v62
	v_exp_f32_e32 v68, v67
	v_mul_f32_e32 v67, 0xbfb8aa3b, v63
	v_mul_f32_e32 v70, 0xbfb8aa3b, v64
	v_exp_f32_e32 v69, v67
	v_exp_f32_e32 v71, v70
	v_mul_f32_e32 v70, 0xbfb8aa3b, v65
	v_exp_f32_e32 v72, v70
	v_add_f32_e32 v69, 1.0, v69
	v_add_f32_e32 v68, 1.0, v68
	v_rcp_f32_e32 v70, v69
	v_add_f32_e32 v69, 1.0, v71
	v_add_f32_e32 v71, 1.0, v72
	v_rcp_f32_e32 v68, v68
	v_rcp_f32_e32 v69, v69
	v_rcp_f32_e32 v71, v71
	v_mov_b32_e32 v72, v62
	v_mov_b32_e32 v73, v64
	v_mov_b32_e32 v64, v63
	v_pk_mul_f32 v[68:69], v[72:73], v[68:69]
	v_mov_b32_e32 v73, v60
	v_pk_mul_f32 v[62:63], v[64:65], v[70:71]
	v_mov_b32_e32 v60, v59
	v_mov_b32_e32 v72, v58
	v_pk_mul_f32 v[58:59], v[60:61], v[62:63]
	v_pk_mul_f32 v[68:69], v[72:73], v[68:69]
	v_and_b32_sdwa v62, v59, v177 dst_sel:DWORD dst_unused:UNUSED_PAD src0_sel:WORD_1 src1_sel:DWORD
	v_and_b32_sdwa v60, v69, v177 dst_sel:DWORD dst_unused:UNUSED_PAD src0_sel:WORD_1 src1_sel:DWORD
	v_and_b32_sdwa v63, v58, v177 dst_sel:DWORD dst_unused:UNUSED_PAD src0_sel:WORD_1 src1_sel:DWORD
	v_add3_u32 v59, v59, v62, s28
	v_and_b32_sdwa v61, v68, v177 dst_sel:DWORD dst_unused:UNUSED_PAD src0_sel:WORD_1 src1_sel:DWORD
	v_add3_u32 v60, v69, v60, s28
	v_add3_u32 v58, v58, v63, s28
	v_and_b32_e32 v59, 0xffff0000, v59
	v_add3_u32 v61, v68, v61, s28
	v_and_b32_e32 v58, 0xffff0000, v58
	v_or_b32_sdwa v59, v59, v60 dst_sel:DWORD dst_unused:UNUSED_PAD src0_sel:DWORD src1_sel:WORD_1
	v_mul_f32_e32 v60, 0xbfb8aa3b, v54
	v_or_b32_sdwa v58, v58, v61 dst_sel:DWORD dst_unused:UNUSED_PAD src0_sel:DWORD src1_sel:WORD_1
	v_exp_f32_e32 v60, v60
	v_mul_f32_e32 v61, 0xbfb8aa3b, v55
	v_or_b32_e32 v66, 32, v110
	v_exp_f32_e32 v61, v61
	v_mad_i64_i32 v[66:67], s[6:7], v66, s52, v[106:107]
	v_lshl_add_u64 v[66:67], v[66:67], 0, v[108:109]
	global_store_dwordx2 v[66:67], v[58:59], off
	v_add_f32_e32 v58, 1.0, v60
	v_mul_f32_e32 v60, 0xbfb8aa3b, v56
	v_add_f32_e32 v59, 1.0, v61
	v_exp_f32_e32 v61, v60
	v_mul_f32_e32 v60, 0xbfb8aa3b, v57
	v_exp_f32_e32 v62, v60
	v_rcp_f32_e32 v60, v59
	v_add_f32_e32 v59, 1.0, v61
	v_rcp_f32_e32 v58, v58
	v_add_f32_e32 v61, 1.0, v62
	v_rcp_f32_e32 v59, v59
	v_rcp_f32_e32 v61, v61
	v_mov_b32_e32 v62, v54
	v_mov_b32_e32 v63, v56
	v_mov_b32_e32 v56, v55
	v_pk_mul_f32 v[58:59], v[62:63], v[58:59]
	v_mov_b32_e32 v63, v52
	v_pk_mul_f32 v[54:55], v[56:57], v[60:61]
	v_mov_b32_e32 v52, v51
	v_mov_b32_e32 v62, v50
	v_pk_mul_f32 v[50:51], v[52:53], v[54:55]
	v_pk_mul_f32 v[58:59], v[62:63], v[58:59]
	v_and_b32_sdwa v54, v51, v177 dst_sel:DWORD dst_unused:UNUSED_PAD src0_sel:WORD_1 src1_sel:DWORD
	v_and_b32_sdwa v52, v59, v177 dst_sel:DWORD dst_unused:UNUSED_PAD src0_sel:WORD_1 src1_sel:DWORD
	v_and_b32_sdwa v55, v50, v177 dst_sel:DWORD dst_unused:UNUSED_PAD src0_sel:WORD_1 src1_sel:DWORD
	v_add3_u32 v51, v51, v54, s28
	v_and_b32_sdwa v53, v58, v177 dst_sel:DWORD dst_unused:UNUSED_PAD src0_sel:WORD_1 src1_sel:DWORD
	v_add3_u32 v52, v59, v52, s28
	v_add3_u32 v50, v50, v55, s28
	v_and_b32_e32 v51, 0xffff0000, v51
	v_add3_u32 v53, v58, v53, s28
	v_and_b32_e32 v50, 0xffff0000, v50
	v_or_b32_sdwa v51, v51, v52 dst_sel:DWORD dst_unused:UNUSED_PAD src0_sel:DWORD src1_sel:WORD_1
	v_mul_f32_e32 v52, 0xbfb8aa3b, v46
	v_or_b32_sdwa v50, v50, v53 dst_sel:DWORD dst_unused:UNUSED_PAD src0_sel:DWORD src1_sel:WORD_1
	v_exp_f32_e32 v52, v52
	v_mul_f32_e32 v53, 0xbfb8aa3b, v47
	v_exp_f32_e32 v53, v53
	global_store_dwordx2 v[66:67], v[50:51], off offset:32
	v_add_f32_e32 v50, 1.0, v52
	v_mul_f32_e32 v52, 0xbfb8aa3b, v48
	v_add_f32_e32 v51, 1.0, v53
	v_exp_f32_e32 v53, v52
	v_mul_f32_e32 v52, 0xbfb8aa3b, v49
	v_exp_f32_e32 v54, v52
	v_rcp_f32_e32 v52, v51
	v_add_f32_e32 v51, 1.0, v53
	v_rcp_f32_e32 v50, v50
	v_add_f32_e32 v53, 1.0, v54
	v_rcp_f32_e32 v51, v51
	v_rcp_f32_e32 v53, v53
	v_mov_b32_e32 v54, v46
	v_mov_b32_e32 v55, v48
	v_mov_b32_e32 v48, v47
	v_pk_mul_f32 v[50:51], v[54:55], v[50:51]
	v_mov_b32_e32 v55, v44
	v_pk_mul_f32 v[46:47], v[48:49], v[52:53]
	v_mov_b32_e32 v44, v43
	v_mov_b32_e32 v54, v42
	v_pk_mul_f32 v[42:43], v[44:45], v[46:47]
	v_pk_mul_f32 v[50:51], v[54:55], v[50:51]
	v_and_b32_sdwa v46, v43, v177 dst_sel:DWORD dst_unused:UNUSED_PAD src0_sel:WORD_1 src1_sel:DWORD
	v_and_b32_sdwa v44, v51, v177 dst_sel:DWORD dst_unused:UNUSED_PAD src0_sel:WORD_1 src1_sel:DWORD
	v_and_b32_sdwa v47, v42, v177 dst_sel:DWORD dst_unused:UNUSED_PAD src0_sel:WORD_1 src1_sel:DWORD
	v_add3_u32 v43, v43, v46, s28
	v_and_b32_sdwa v45, v50, v177 dst_sel:DWORD dst_unused:UNUSED_PAD src0_sel:WORD_1 src1_sel:DWORD
	v_add3_u32 v44, v51, v44, s28
	v_add3_u32 v42, v42, v47, s28
	v_and_b32_e32 v43, 0xffff0000, v43
	v_add3_u32 v45, v50, v45, s28
	v_and_b32_e32 v42, 0xffff0000, v42
	v_or_b32_sdwa v43, v43, v44 dst_sel:DWORD dst_unused:UNUSED_PAD src0_sel:DWORD src1_sel:WORD_1
	v_mul_f32_e32 v44, 0xbfb8aa3b, v38
	v_or_b32_sdwa v42, v42, v45 dst_sel:DWORD dst_unused:UNUSED_PAD src0_sel:DWORD src1_sel:WORD_1
	v_exp_f32_e32 v44, v44
	v_mul_f32_e32 v45, 0xbfb8aa3b, v39
	v_exp_f32_e32 v45, v45
	global_store_dwordx2 v[66:67], v[42:43], off offset:64
	v_add_f32_e32 v42, 1.0, v44
	v_mul_f32_e32 v44, 0xbfb8aa3b, v40
	v_add_f32_e32 v43, 1.0, v45
	v_exp_f32_e32 v45, v44
	v_mul_f32_e32 v44, 0xbfb8aa3b, v41
	v_exp_f32_e32 v46, v44
	v_rcp_f32_e32 v44, v43
	v_add_f32_e32 v43, 1.0, v45
	v_rcp_f32_e32 v42, v42
	v_add_f32_e32 v45, 1.0, v46
	v_rcp_f32_e32 v43, v43
	v_rcp_f32_e32 v45, v45
	v_mov_b32_e32 v46, v38
	v_mov_b32_e32 v47, v40
	v_mov_b32_e32 v40, v39
	v_pk_mul_f32 v[42:43], v[46:47], v[42:43]
	v_mov_b32_e32 v47, v36
	v_pk_mul_f32 v[38:39], v[40:41], v[44:45]
	v_mov_b32_e32 v36, v35
	v_mov_b32_e32 v46, v34
	v_pk_mul_f32 v[34:35], v[36:37], v[38:39]
	v_pk_mul_f32 v[42:43], v[46:47], v[42:43]
	v_and_b32_sdwa v38, v35, v177 dst_sel:DWORD dst_unused:UNUSED_PAD src0_sel:WORD_1 src1_sel:DWORD
	v_and_b32_sdwa v39, v34, v177 dst_sel:DWORD dst_unused:UNUSED_PAD src0_sel:WORD_1 src1_sel:DWORD
	v_and_b32_sdwa v36, v43, v177 dst_sel:DWORD dst_unused:UNUSED_PAD src0_sel:WORD_1 src1_sel:DWORD
	v_and_b32_sdwa v37, v42, v177 dst_sel:DWORD dst_unused:UNUSED_PAD src0_sel:WORD_1 src1_sel:DWORD
	v_add3_u32 v35, v35, v38, s28
	v_add3_u32 v34, v34, v39, s28
	v_add3_u32 v37, v42, v37, s28
	v_add3_u32 v36, v43, v36, s28
	v_and_b32_e32 v35, 0xffff0000, v35
	v_and_b32_e32 v34, 0xffff0000, v34
	v_or_b32_sdwa v35, v35, v36 dst_sel:DWORD dst_unused:UNUSED_PAD src0_sel:DWORD src1_sel:WORD_1
	v_or_b32_sdwa v34, v34, v37 dst_sel:DWORD dst_unused:UNUSED_PAD src0_sel:DWORD src1_sel:WORD_1
	global_store_dwordx2 v[66:67], v[34:35], off offset:96
	v_mul_f32_e32 v35, 0xbfb8aa3b, v30
	v_exp_f32_e32 v36, v35
	v_mul_f32_e32 v35, 0xbfb8aa3b, v31
	v_mul_f32_e32 v38, 0xbfb8aa3b, v32
	v_exp_f32_e32 v37, v35
	v_exp_f32_e32 v39, v38
	v_mul_f32_e32 v38, 0xbfb8aa3b, v33
	v_exp_f32_e32 v40, v38
	v_add_f32_e32 v37, 1.0, v37
	v_add_f32_e32 v36, 1.0, v36
	v_rcp_f32_e32 v38, v37
	v_add_f32_e32 v37, 1.0, v39
	v_add_f32_e32 v39, 1.0, v40
	v_rcp_f32_e32 v36, v36
	v_rcp_f32_e32 v37, v37
	v_rcp_f32_e32 v39, v39
	v_mov_b32_e32 v40, v30
	v_mov_b32_e32 v41, v32
	v_mov_b32_e32 v32, v31
	v_pk_mul_f32 v[36:37], v[40:41], v[36:37]
	v_mov_b32_e32 v41, v28
	v_pk_mul_f32 v[30:31], v[32:33], v[38:39]
	v_mov_b32_e32 v28, v27
	v_mov_b32_e32 v40, v26
	v_pk_mul_f32 v[26:27], v[28:29], v[30:31]
	v_pk_mul_f32 v[36:37], v[40:41], v[36:37]
	v_and_b32_sdwa v30, v27, v177 dst_sel:DWORD dst_unused:UNUSED_PAD src0_sel:WORD_1 src1_sel:DWORD
	v_and_b32_sdwa v28, v37, v177 dst_sel:DWORD dst_unused:UNUSED_PAD src0_sel:WORD_1 src1_sel:DWORD
	v_and_b32_sdwa v31, v26, v177 dst_sel:DWORD dst_unused:UNUSED_PAD src0_sel:WORD_1 src1_sel:DWORD
	v_add3_u32 v27, v27, v30, s28
	v_and_b32_sdwa v29, v36, v177 dst_sel:DWORD dst_unused:UNUSED_PAD src0_sel:WORD_1 src1_sel:DWORD
	v_add3_u32 v28, v37, v28, s28
	v_add3_u32 v26, v26, v31, s28
	v_and_b32_e32 v27, 0xffff0000, v27
	v_add3_u32 v29, v36, v29, s28
	v_and_b32_e32 v26, 0xffff0000, v26
	v_or_b32_sdwa v27, v27, v28 dst_sel:DWORD dst_unused:UNUSED_PAD src0_sel:DWORD src1_sel:WORD_1
	v_mul_f32_e32 v28, 0xbfb8aa3b, v22
	v_or_b32_sdwa v26, v26, v29 dst_sel:DWORD dst_unused:UNUSED_PAD src0_sel:DWORD src1_sel:WORD_1
	v_exp_f32_e32 v28, v28
	v_mul_f32_e32 v29, 0xbfb8aa3b, v23
	v_or_b32_e32 v34, 48, v110
	v_exp_f32_e32 v29, v29
	v_mad_i64_i32 v[34:35], s[6:7], v34, s52, v[106:107]
	v_lshl_add_u64 v[34:35], v[34:35], 0, v[108:109]
	global_store_dwordx2 v[34:35], v[26:27], off
	v_add_f32_e32 v26, 1.0, v28
	v_mul_f32_e32 v28, 0xbfb8aa3b, v24
	v_add_f32_e32 v27, 1.0, v29
	v_exp_f32_e32 v29, v28
	v_mul_f32_e32 v28, 0xbfb8aa3b, v25
	v_exp_f32_e32 v30, v28
	v_rcp_f32_e32 v28, v27
	v_add_f32_e32 v27, 1.0, v29
	v_rcp_f32_e32 v26, v26
	v_add_f32_e32 v29, 1.0, v30
	v_rcp_f32_e32 v27, v27
	v_rcp_f32_e32 v29, v29
	v_mov_b32_e32 v30, v22
	v_mov_b32_e32 v31, v24
	v_mov_b32_e32 v24, v23
	v_pk_mul_f32 v[26:27], v[30:31], v[26:27]
	v_mov_b32_e32 v31, v20
	v_pk_mul_f32 v[22:23], v[24:25], v[28:29]
	v_mov_b32_e32 v20, v19
	v_mov_b32_e32 v30, v18
	v_pk_mul_f32 v[18:19], v[20:21], v[22:23]
	v_pk_mul_f32 v[26:27], v[30:31], v[26:27]
	v_and_b32_sdwa v22, v19, v177 dst_sel:DWORD dst_unused:UNUSED_PAD src0_sel:WORD_1 src1_sel:DWORD
	v_and_b32_sdwa v20, v27, v177 dst_sel:DWORD dst_unused:UNUSED_PAD src0_sel:WORD_1 src1_sel:DWORD
	v_and_b32_sdwa v23, v18, v177 dst_sel:DWORD dst_unused:UNUSED_PAD src0_sel:WORD_1 src1_sel:DWORD
	v_add3_u32 v19, v19, v22, s28
	v_and_b32_sdwa v21, v26, v177 dst_sel:DWORD dst_unused:UNUSED_PAD src0_sel:WORD_1 src1_sel:DWORD
	v_add3_u32 v20, v27, v20, s28
	v_add3_u32 v18, v18, v23, s28
	v_and_b32_e32 v19, 0xffff0000, v19
	v_add3_u32 v21, v26, v21, s28
	v_and_b32_e32 v18, 0xffff0000, v18
	v_or_b32_sdwa v19, v19, v20 dst_sel:DWORD dst_unused:UNUSED_PAD src0_sel:DWORD src1_sel:WORD_1
	v_mul_f32_e32 v20, 0xbfb8aa3b, v14
	v_or_b32_sdwa v18, v18, v21 dst_sel:DWORD dst_unused:UNUSED_PAD src0_sel:DWORD src1_sel:WORD_1
	v_exp_f32_e32 v20, v20
	v_mul_f32_e32 v21, 0xbfb8aa3b, v15
	v_exp_f32_e32 v21, v21
	global_store_dwordx2 v[34:35], v[18:19], off offset:32
	v_add_f32_e32 v18, 1.0, v20
	v_mul_f32_e32 v20, 0xbfb8aa3b, v16
	v_add_f32_e32 v19, 1.0, v21
	v_exp_f32_e32 v21, v20
	v_mul_f32_e32 v20, 0xbfb8aa3b, v17
	v_exp_f32_e32 v22, v20
	v_rcp_f32_e32 v20, v19
	v_add_f32_e32 v19, 1.0, v21
	v_rcp_f32_e32 v18, v18
	v_add_f32_e32 v21, 1.0, v22
	v_rcp_f32_e32 v19, v19
	v_rcp_f32_e32 v21, v21
	v_mov_b32_e32 v22, v14
	v_mov_b32_e32 v23, v16
	v_mov_b32_e32 v16, v15
	v_pk_mul_f32 v[18:19], v[22:23], v[18:19]
	v_mov_b32_e32 v23, v12
	v_pk_mul_f32 v[14:15], v[16:17], v[20:21]
	v_mov_b32_e32 v12, v11
	v_mov_b32_e32 v22, v10
	v_pk_mul_f32 v[10:11], v[12:13], v[14:15]
	v_pk_mul_f32 v[18:19], v[22:23], v[18:19]
	v_and_b32_sdwa v14, v11, v177 dst_sel:DWORD dst_unused:UNUSED_PAD src0_sel:WORD_1 src1_sel:DWORD
	v_and_b32_sdwa v12, v19, v177 dst_sel:DWORD dst_unused:UNUSED_PAD src0_sel:WORD_1 src1_sel:DWORD
	v_and_b32_sdwa v15, v10, v177 dst_sel:DWORD dst_unused:UNUSED_PAD src0_sel:WORD_1 src1_sel:DWORD
	v_add3_u32 v11, v11, v14, s28
	v_and_b32_sdwa v13, v18, v177 dst_sel:DWORD dst_unused:UNUSED_PAD src0_sel:WORD_1 src1_sel:DWORD
	v_add3_u32 v12, v19, v12, s28
	v_add3_u32 v10, v10, v15, s28
	v_and_b32_e32 v11, 0xffff0000, v11
	v_add3_u32 v13, v18, v13, s28
	v_and_b32_e32 v10, 0xffff0000, v10
	v_or_b32_sdwa v11, v11, v12 dst_sel:DWORD dst_unused:UNUSED_PAD src0_sel:DWORD src1_sel:WORD_1
	v_mul_f32_e32 v12, 0xbfb8aa3b, v6
	v_or_b32_sdwa v10, v10, v13 dst_sel:DWORD dst_unused:UNUSED_PAD src0_sel:DWORD src1_sel:WORD_1
	v_exp_f32_e32 v12, v12
	v_mul_f32_e32 v13, 0xbfb8aa3b, v7
	v_exp_f32_e32 v13, v13
	global_store_dwordx2 v[34:35], v[10:11], off offset:64
	v_add_f32_e32 v10, 1.0, v12
	v_mul_f32_e32 v12, 0xbfb8aa3b, v8
	v_add_f32_e32 v11, 1.0, v13
	v_exp_f32_e32 v13, v12
	v_mul_f32_e32 v12, 0xbfb8aa3b, v9
	v_exp_f32_e32 v14, v12
	v_rcp_f32_e32 v12, v11
	v_add_f32_e32 v11, 1.0, v13
	v_rcp_f32_e32 v10, v10
	v_add_f32_e32 v13, 1.0, v14
	v_rcp_f32_e32 v11, v11
	v_rcp_f32_e32 v13, v13
	v_mov_b32_e32 v14, v6
	v_mov_b32_e32 v15, v8
	v_mov_b32_e32 v8, v7
	v_pk_mul_f32 v[10:11], v[14:15], v[10:11]
	v_mov_b32_e32 v15, v4
	v_pk_mul_f32 v[6:7], v[8:9], v[12:13]
	v_mov_b32_e32 v4, v3
	v_mov_b32_e32 v14, v2
	v_pk_mul_f32 v[2:3], v[4:5], v[6:7]
	v_pk_mul_f32 v[10:11], v[14:15], v[10:11]
	v_and_b32_sdwa v6, v3, v177 dst_sel:DWORD dst_unused:UNUSED_PAD src0_sel:WORD_1 src1_sel:DWORD
	v_and_b32_sdwa v7, v2, v177 dst_sel:DWORD dst_unused:UNUSED_PAD src0_sel:WORD_1 src1_sel:DWORD
	v_and_b32_sdwa v4, v11, v177 dst_sel:DWORD dst_unused:UNUSED_PAD src0_sel:WORD_1 src1_sel:DWORD
	v_and_b32_sdwa v5, v10, v177 dst_sel:DWORD dst_unused:UNUSED_PAD src0_sel:WORD_1 src1_sel:DWORD
	v_add3_u32 v3, v3, v6, s28
	v_add3_u32 v2, v2, v7, s28
	v_add3_u32 v5, v10, v5, s28
	v_add3_u32 v4, v11, v4, s28
	v_and_b32_e32 v3, 0xffff0000, v3
	v_and_b32_e32 v2, 0xffff0000, v2
	s_add_i32 s20, s20, s11
	v_or_b32_sdwa v3, v3, v4 dst_sel:DWORD dst_unused:UNUSED_PAD src0_sel:DWORD src1_sel:WORD_1
	v_or_b32_sdwa v2, v2, v5 dst_sel:DWORD dst_unused:UNUSED_PAD src0_sel:DWORD src1_sel:WORD_1
	s_cmpk_gt_i32 s20, 0x5ff
	global_store_dwordx2 v[34:35], v[2:3], off offset:96
	s_cbranch_scc0 .LBB0_465
